# strategy 7.4a per-half A/B: static s_setprio 1 for waves 0-3 (instead of 4-7) in the attention main loop
# baseline (speedup 1.0000x reference)
; #define LAS __attribute__((address_space(3)))
; template <int NQB> ...
;     ...
;     LAS bf16x8* qlds = (LAS bf16x8*)((LAS unsigned char*)red + 4096 + h * 12288) + lane;
; #pragma unroll
;     for (int qb = 0; qb < NQB; ++qb)
; #pragma unroll
;         for (int s = 0; s < 6; ++s) qlds[(qb * 6 + s) * 64] = *(const bf16x8*)(Q + (size_t)(qrow0 + 32 * qb + r) * 768 + h * 96 + 16 * s + 8 * hh);
;     f32x16 O[NQB][2]; float mrun[NQB], lrun[NQB];
; #pragma unroll
;     for (int qb = 0; qb < NQB; ++qb) { mrun[qb] = -1e30f; lrun[qb] = 0.f;
; #pragma unroll
;         for (int db = 0; db < 2; ++db)
; #pragma unroll
;             for (int i = 0; i < 16; ++i) O[qb][db][i] = 0.f; }
;     const int pr = (r & 0x13) | ((r & 4) << 1) | ((r & 8) >> 1);
;     const int blk0 = kvrow0 >> 5; (void)pr;
;     const bf16_t* kp = Kn + ((size_t)(blk0 * 8 + h) * 256 + lane) * 8;
;     const bf16_t* krp = Kr + ((size_t)blk0 * 128 + lane) * 8;
;     const bf16_t* vp = VT + ((size_t)(blk0 * 8 + h) * 256 + lane) * 8;
;     bf16x8 Kf[6];
; #pragma unroll
;     for (int s = 0; s < 4; ++s) Kf[s] = *(const bf16x8*)(kp + 512 * s);
;     Kf[4] = *(const bf16x8*)(krp); Kf[5] = *(const bf16x8*)(krp + 512);
; __global__ void __launch_bounds__(512, 2) fwd_megakernel(Args a_) {
;     ...
;                         if (tid == 0) *slot = (int)__hip_atomic_fetch_add(ctr, 1u, __ATOMIC_RELAXED, __HIP_MEMORY_SCOPE_AGENT);
;                         __syncthreads();
;                         const int u = *slot;
;                         __syncthreads();
;                         if (u >= 129) break;
;     ...
;                         if (u == 0) attn_unit<1>(qbuf, Knb, krb, VTb, A3, NP + x * 32, NP + x * 4128, 129, wave, lane, red);
;                         else { const int i = u - 1, b = x + 8 * (i >> 5), c = 31 - (i & 31); attn_unit<2>(qbuf, Knb, krb, VTb, A3, b * 2048 + 64 * c, b * 2048, 2 * (c + 1), wave, lane, red); }
.LBB0_83:
	s_or_b64 exec, exec, s[4:5]
	s_waitcnt lgkmcnt(0)
	s_barrier
	ds_read_b32 v0, v133 offset:2048
	s_movk_i32 s1, 0x80
	s_mov_b64 s[4:5], -1
	s_waitcnt lgkmcnt(0)
	s_barrier
	v_cmp_lt_i32_e32 vcc, s1, v0
	v_readfirstlane_b32 s0, v0
	s_cbranch_vccnz .LBB0_78
	s_mul_i32 s1, s81, 0x3000
	s_cmp_lg_u32 s0, 0
	v_add_u32_e32 v194, s1, v129
	s_cbranch_scc0 .LBB0_92
	s_add_i32 s0, s0, -1
	s_ashr_i32 s20, s0, 2
	s_and_b32 s1, s20, -8
	s_or_b32 s4, s1, s58
	s_and_b32 s0, s0, 31
	s_lshl_b32 s1, s4, 11
	s_lshl_b32 s5, s0, 6
	s_or_b32 s1, s1, s5
	v_bitop3_b32 v162, s1, v182, v169 bitop3:0x36
	s_lshl_b32 s21, s0, 1
	v_or_b32_e32 v6, s1, v169
	v_mad_i64_i32 v[4:5], s[0:1], v162, s78, v[126:127]
	global_load_dwordx4 v[8:11], v[4:5], off
	v_bitop3_b32 v160, v6, 32, v182 bitop3:0xde
	v_ashrrev_i32_e32 v163, 31, v162
	v_ashrrev_i32_e32 v161, 31, v160
	v_mov_b32_e32 v195, 0xf149f2ca
	s_mov_b64 s[44:45], 0
	v_mov_b32_e32 v196, 0xf149f2ca
	global_load_dwordx4 v[12:15], v[4:5], off offset:32
	global_load_dwordx4 v[16:19], v[4:5], off offset:64
	global_load_dwordx4 v[20:23], v[4:5], off offset:96
	global_load_dwordx4 v[24:27], v[4:5], off offset:128
	global_load_dwordx4 v[28:31], v[4:5], off offset:160
	v_mad_i64_i32 v[4:5], s[0:1], v160, s78, v[126:127]
	s_lshl_b32 s1, s4, 9
	s_lshl_b32 s0, s4, 6
	s_add_i32 s4, s1, s81
	s_ashr_i32 s5, s4, 31
	s_lshl_b64 s[4:5], s[4:5], 11
	v_mov_b32_e32 v167, s5
	v_or_b32_e32 v166, s4, v128
	s_ashr_i32 s1, s0, 31
	s_lshl_b64 s[0:1], s[0:1], 11
	global_load_dwordx4 v[32:35], v[4:5], off
	global_load_dwordx4 v[36:39], v[4:5], off offset:32
	global_load_dwordx4 v[40:43], v[4:5], off offset:64
	global_load_dwordx4 v[44:47], v[4:5], off offset:96
	global_load_dwordx4 v[48:51], v[4:5], off offset:128
	global_load_dwordx4 v[52:55], v[4:5], off offset:160
	s_waitcnt vmcnt(0)
	ds_write_b128 v194, v[8:11] offset:4096
	ds_write_b128 v194, v[12:15] offset:5120
	ds_write_b128 v194, v[16:19] offset:6144
	ds_write_b128 v194, v[20:23] offset:7168
	ds_write_b128 v194, v[24:27] offset:8192
	ds_write_b128 v194, v[28:31] offset:9216
	ds_write_b128 v194, v[32:35] offset:10240
	ds_write_b128 v194, v[36:39] offset:11264
	ds_write_b128 v194, v[40:43] offset:12288
	ds_write_b128 v194, v[44:47] offset:13312
	ds_write_b128 v194, v[48:51] offset:14336
	ds_write_b128 v194, v[52:55] offset:15360
	v_lshl_add_u64 v[0:1], v[166:167], 1, s[34:35]
	v_lshl_add_u64 v[2:3], v[130:131], 0, s[0:1]
	global_load_dwordx4 v[116:119], v[0:1], off
	global_load_dwordx4 v[112:115], v[0:1], off offset:1024
	global_load_dwordx4 v[108:111], v[0:1], off offset:2048
	global_load_dwordx4 v[104:107], v[0:1], off offset:3072
	global_load_dwordx4 v[100:103], v[2:3], off
	global_load_dwordx4 v[96:99], v[2:3], off offset:1024
	s_lshr_b32 s1, s20, 3
	s_lshl_b32 s4, s1, 9
	s_or_b32 s4, s47, s4
	s_ashr_i32 s5, s4, 31
	s_xor_b32 s0, s21, 63
	s_lshl_b64 s[4:5], s[4:5], 11
	s_add_u32 s4, s54, s4
	s_addc_u32 s5, s55, s5
	s_lshl_b32 s1, s1, 12
	s_add_i32 s20, s59, s1
	s_ashr_i32 s21, s20, 31
	s_lshl_b64 s[20:21], s[20:21], 12
	s_add_u32 s20, s54, s20
	v_mov_b32_e32 v0, 0
	s_addc_u32 s21, s55, s21
	v_mov_b32_e32 v1, v0
	v_mov_b32_e32 v2, v0
	v_mov_b32_e32 v3, v0
	v_mov_b32_e32 v4, v0
	v_mov_b32_e32 v5, v0
	v_mov_b32_e32 v6, v0
	v_mov_b32_e32 v7, v0
	v_mov_b32_e32 v8, v0
	v_mov_b32_e32 v9, v0
	v_mov_b32_e32 v10, v0
	v_mov_b32_e32 v11, v0
	v_mov_b32_e32 v12, v0
	v_mov_b32_e32 v13, v0
	v_mov_b32_e32 v14, v0
	v_mov_b32_e32 v15, v0
	v_mov_b32_e32 v16, v0
	v_mov_b32_e32 v17, v0
	v_mov_b32_e32 v18, v0
	v_mov_b32_e32 v19, v0
	v_mov_b32_e32 v20, v0
	v_mov_b32_e32 v21, v0
	v_mov_b32_e32 v22, v0
	v_mov_b32_e32 v23, v0
	v_mov_b32_e32 v24, v0
	v_mov_b32_e32 v25, v0
	v_mov_b32_e32 v26, v0
	v_mov_b32_e32 v27, v0
	v_mov_b32_e32 v28, v0
	v_mov_b32_e32 v29, v0
	v_mov_b32_e32 v30, v0
	v_mov_b32_e32 v31, v0
	v_mov_b32_e32 v32, v0
	v_mov_b32_e32 v33, v0
	v_mov_b32_e32 v34, v0
	v_mov_b32_e32 v35, v0
	v_mov_b32_e32 v36, v0
	v_mov_b32_e32 v37, v0
	v_mov_b32_e32 v38, v0
	v_mov_b32_e32 v39, v0
	v_mov_b32_e32 v40, v0
	v_mov_b32_e32 v41, v0
	v_mov_b32_e32 v42, v0
	v_mov_b32_e32 v43, v0
	v_mov_b32_e32 v44, v0
	v_mov_b32_e32 v45, v0
	v_mov_b32_e32 v46, v0
	v_mov_b32_e32 v47, v0
	v_mov_b32_e32 v48, v0
	v_mov_b32_e32 v49, v0
	v_mov_b32_e32 v50, v0
	v_mov_b32_e32 v51, v0
	v_mov_b32_e32 v52, v0
	v_mov_b32_e32 v53, v0
	v_mov_b32_e32 v54, v0
	v_mov_b32_e32 v55, v0
	v_mov_b32_e32 v56, v0
	v_mov_b32_e32 v57, v0
	v_mov_b32_e32 v58, v0
	v_mov_b32_e32 v59, v0
	v_mov_b32_e32 v60, v0
	v_mov_b32_e32 v61, v0
	v_mov_b32_e32 v62, v0
	v_mov_b32_e32 v63, v0
	v_mov_b32_e32 v164, v0
	v_mov_b32_e32 v165, v0
	s_cmp_ge_u32 s81, 4
	s_cbranch_scc1 .Lprio_skip
	s_setprio 1
